# attention: pipelined LDS fragment reads + DMA interleave; unit prologue Q loads overlap first DMA; gla_out first wait counted
# speedup vs baseline: 1.0278x; 1.0031x over previous
; #define MFMA32(a, b, c) __builtin_amdgcn_mfma_f32_32x32x16_bf16((a), (b), (c), 0, 0, 0)
;     ...
;     for (int u = vb; u < 2048; u += nb) {
;         const int cidx = u >> 2, hh = u & 3, tok0 = cidx * 64;
;         bf16x8 bfr[8], afr[2][8];
; #pragma unroll
;         for (int ks = 0; ks < 8; ++ks) {
;             bfr[ks] = *(const bf16x8*)(ST + (((size_t)(cidx * 4 + hh)) * 256 + 32 * w + li) * 128 + ks * 16 + h * 8);
; #pragma unroll
;             for (int mi = 0; mi < 2; ++mi) afr[mi][ks] = *(const bf16x8*)(GQ + (size_t)(tok0 + mi * 32 + li) * 512 + hh * 128 + ks * 16 + h * 8);
;         }
;         f32x4 gn[4]; u32x2 rr[2][4];
; #pragma unroll
;         for (int g = 0; g < 4; ++g) {
;             const int v0 = hh * 256 + 32 * w + 8 * g + 4 * h;
;             gn[g] = *(const f32x4*)(on + v0);
; #pragma unroll
;             for (int mi = 0; mi < 2; ++mi) rr[mi][g] = *(const u32x2*)(GR + (size_t)(tok0 + mi * 32 + li) * 1024 + v0);
;         }
;         f32x16 acc[2];
; #pragma unroll
;         for (int mi = 0; mi < 2; ++mi)
; #pragma unroll
;             for (int i = 0; i < 16; ++i) acc[mi][i] = 0.f;
; #pragma unroll
;         for (int ks = 0; ks < 8; ++ks)
; #pragma unroll
;             for (int mi = 0; mi < 2; ++mi) acc[mi] = MFMA32(bfr[ks], afr[mi][ks], acc[mi]);
; #pragma unroll
;         for (int mi = 0; mi < 2; ++mi) {
;             float s1 = 0.f, s2 = 0.f;
; #pragma unroll
;             for (int i = 0; i < 16; ++i) { s1 += acc[mi][i]; s2 += acc[mi][i] * acc[mi][i]; }
;             s1 += __shfl_xor(s1, 32); s2 += __shfl_xor(s2, 32);
;             if (h == 0) red[w * 64 + mi * 32 + li] = (f32x2){s1, s2};
.LBB0_498:
	s_and_b32 s1, s20, 0xffffffc0
	v_or_b32_e32 v76, s1, v78
	s_lshl_b32 s1, s0, 8
	global_load_dwordx4 v[0:3], v[50:51], off offset:-128
	s_and_b32 s28, s1, 0x300
	v_ashrrev_i32_e32 v77, 31, v76
	v_lshl_add_u64 v[8:9], v[48:49], 0, s[28:29]
	v_lshlrev_b64 v[4:5], 10, v[76:77]
	v_lshl_add_u64 v[104:105], v[8:9], 0, v[4:5]
	global_load_dwordx4 v[4:7], v[104:105], off
	v_or_b32_e32 v108, 32, v76
	v_ashrrev_i32_e32 v109, 31, v108
	v_lshlrev_b64 v[10:11], 10, v[108:109]
	v_lshl_add_u64 v[110:111], v[8:9], 0, v[10:11]
	global_load_dwordx4 v[8:11], v[110:111], off
	global_load_dwordx4 v[32:35], v[50:51], off offset:-96
	global_load_dwordx4 v[36:39], v[104:105], off offset:32
	global_load_dwordx4 v[40:43], v[110:111], off offset:32
	global_load_dwordx4 v[44:47], v[50:51], off offset:-64
	global_load_dwordx4 v[52:55], v[104:105], off offset:64
	global_load_dwordx4 v[56:59], v[110:111], off offset:64
	global_load_dwordx4 v[60:63], v[50:51], off offset:-32
	global_load_dwordx4 v[64:67], v[104:105], off offset:96
	global_load_dwordx4 v[68:71], v[110:111], off offset:96
	global_load_dwordx4 v[72:75], v[50:51], off
	v_readlane_b32 s18, v254, 30
	v_readlane_b32 s19, v254, 31
	s_waitcnt vmcnt(11)
	v_mfma_f32_32x32x16_bf16 v[16:31], v[0:3], v[4:7], 0
	s_waitcnt vmcnt(10)
	v_mfma_f32_32x32x16_bf16 v[0:15], v[0:3], v[8:11], 0
	s_waitcnt vmcnt(8)
	v_mfma_f32_32x32x16_bf16 v[16:31], v[32:35], v[36:39], v[16:31]
	global_load_dwordx4 v[36:39], v[104:105], off offset:128
	s_waitcnt vmcnt(8)
	v_mfma_f32_32x32x16_bf16 v[0:15], v[32:35], v[40:43], v[0:15]
	global_load_dwordx4 v[32:35], v[110:111], off offset:128
	global_load_dwordx4 v[84:87], v[50:51], off offset:32
	global_load_dwordx4 v[40:43], v[104:105], off offset:160
	s_waitcnt vmcnt(9)
	v_mfma_f32_32x32x16_bf16 v[16:31], v[44:47], v[52:55], v[16:31]
	global_load_dwordx4 v[52:55], v[110:111], off offset:160
	global_load_dwordx4 v[88:91], v[50:51], off offset:64
	global_load_dwordx4 v[92:95], v[104:105], off offset:192
	global_load_dwordx4 v[96:99], v[110:111], off offset:192
	global_load_dwordx4 v[100:103], v[50:51], off offset:96
	s_nop 0
	global_load_dwordx4 v[104:107], v[104:105], off offset:224
	s_waitcnt vmcnt(14)
	v_mfma_f32_32x32x16_bf16 v[0:15], v[44:47], v[56:59], v[0:15]
	v_lshlrev_b64 v[56:57], 11, v[108:109]
	s_waitcnt vmcnt(12)
	v_mfma_f32_32x32x16_bf16 v[16:31], v[60:63], v[64:67], v[16:31]
	v_add_u32_e32 v64, s28, v80
	v_ashrrev_i32_e32 v65, 31, v64
	v_or_b32_e32 v58, 24, v64
	v_ashrrev_i32_e32 v59, 31, v58
	s_waitcnt vmcnt(11)
	v_mfma_f32_32x32x16_bf16 v[0:15], v[60:63], v[68:71], v[0:15]
	v_lshlrev_b64 v[68:69], 11, v[76:77]
	v_lshl_add_u64 v[60:61], s[18:19], 0, v[68:69]
	s_waitcnt vmcnt(8)
	v_mfma_f32_32x32x16_bf16 v[0:15], v[72:75], v[32:35], v[0:15]
	v_lshl_add_u64 v[32:33], v[64:65], 2, s[8:9]
	v_lshl_add_u64 v[34:35], v[64:65], 1, s[18:19]
	v_lshl_add_u64 v[62:63], v[34:35], 0, v[68:69]
	v_lshl_add_u64 v[66:67], v[34:35], 0, v[56:57]
	v_mfma_f32_32x32x16_bf16 v[16:31], v[72:75], v[36:39], v[16:31]
	v_or_b32_e32 v36, 8, v64
	v_or_b32_e32 v38, 16, v64
	v_ashrrev_i32_e32 v37, 31, v36
	v_ashrrev_i32_e32 v39, 31, v38
	v_lshlrev_b64 v[70:71], 1, v[36:37]
	v_lshlrev_b64 v[74:75], 1, v[38:39]
	v_lshl_add_u64 v[72:73], s[18:19], 0, v[56:57]
	s_waitcnt vmcnt(6)
	v_mfma_f32_32x32x16_bf16 v[16:31], v[84:87], v[40:43], v[16:31]
	global_load_dwordx4 v[44:47], v[32:33], off
	global_load_dwordx4 v[40:43], v[32:33], off offset:32
	global_load_dwordx4 v[36:39], v[32:33], off offset:64
	s_nop 0
	global_load_dwordx4 v[32:35], v[32:33], off offset:96
	v_lshl_add_u64 v[76:77], v[60:61], 0, v[74:75]
	v_lshl_add_u64 v[74:75], v[72:73], 0, v[74:75]
	s_waitcnt vmcnt(9)
	v_mfma_f32_32x32x16_bf16 v[0:15], v[84:87], v[52:55], v[0:15]
	global_load_dwordx4 v[84:87], v[110:111], off offset:224
	v_lshlrev_b64 v[52:53], 1, v[58:59]
	v_lshl_add_u64 v[54:55], v[60:61], 0, v[70:71]
	v_lshl_add_u64 v[58:59], v[72:73], 0, v[70:71]
	s_waitcnt vmcnt(8)
	v_mfma_f32_32x32x16_bf16 v[16:31], v[88:91], v[92:95], v[16:31]
	v_lshl_add_u64 v[92:93], v[60:61], 0, v[52:53]
	v_lshl_add_u64 v[52:53], v[72:73], 0, v[52:53]
	global_load_dwordx2 v[72:73], v[62:63], off
	global_load_dwordx2 v[60:61], v[66:67], off
	global_load_dwordx2 v[70:71], v[54:55], off
	s_nop 0
	global_load_dwordx2 v[58:59], v[58:59], off
	s_nop 0
	global_load_dwordx2 v[66:67], v[76:77], off
	global_load_dwordx2 v[54:55], v[74:75], off
	global_load_dwordx2 v[62:63], v[92:93], off
	s_nop 0
	global_load_dwordx2 v[52:53], v[52:53], off
	s_waitcnt vmcnt(13)
	v_mfma_f32_32x32x16_bf16 v[16:31], v[100:103], v[104:107], v[16:31]
	v_mfma_f32_32x32x16_bf16 v[0:15], v[88:91], v[96:99], v[0:15]
	s_nop 10
	v_add_f32_e32 v83, 0, v16
	v_mul_f32_e32 v98, v17, v17
	v_mul_f32_e64 v74, v30, v30
	v_mul_f32_e64 v75, v31, v31
	v_fmac_f32_e32 v98, v16, v16
	v_add_f32_e32 v75, v17, v83
	v_pk_mul_f32 v[96:97], v[18:19], v[18:19]
	v_add_f32_e32 v75, v18, v75
	v_fmac_f32_e32 v98, v18, v18
	v_pk_mul_f32 v[94:95], v[20:21], v[20:21]
	v_add_f32_e32 v75, v19, v75
	v_add_f32_e32 v83, v97, v98
	v_add_f32_e32 v75, v20, v75
	v_add_f32_e32 v83, v94, v83
	v_pk_mul_f32 v[92:93], v[22:23], v[22:23]
	v_add_f32_e32 v75, v21, v75
	v_add_f32_e32 v83, v95, v83
	v_add_f32_e32 v75, v22, v75
	v_add_f32_e32 v83, v92, v83
	v_pk_mul_f32 v[90:91], v[24:25], v[24:25]
	v_add_f32_e32 v75, v23, v75
	v_add_f32_e32 v83, v93, v83
	v_add_f32_e32 v75, v24, v75
	v_add_f32_e32 v83, v90, v83
	v_pk_mul_f32 v[88:89], v[26:27], v[26:27]
	v_add_f32_e32 v75, v25, v75
	v_add_f32_e32 v83, v91, v83
	v_add_f32_e32 v75, v26, v75
	v_add_f32_e32 v83, v88, v83
	v_pk_mul_f32 v[76:77], v[28:29], v[28:29]
	v_add_f32_e32 v75, v27, v75
	v_add_f32_e32 v83, v89, v83
	v_add_f32_e32 v75, v28, v75
	v_add_f32_e32 v76, v76, v83
	v_add_f32_e32 v75, v29, v75
	v_add_f32_e32 v76, v77, v76
	s_waitcnt vmcnt(8)
	v_mfma_f32_32x32x16_bf16 v[0:15], v[100:103], v[84:87], v[0:15]
	v_mul_f32_e32 v99, v31, v31
	v_mov_b32_e32 v96, v31
	v_add_f32_e32 v98, v30, v75
	v_add_f32_e32 v97, v74, v76
	v_add_f32_e64 v74, v96, v98
	v_add_f32_e64 v75, v97, v99
	ds_bpermute_b32 v76, v81, v74
	ds_bpermute_b32 v77, v81, v75
	s_and_saveexec_b64 s[18:19], vcc
	s_cbranch_execz .LBB0_500
	s_waitcnt lgkmcnt(0)
	v_pk_add_f32 v[74:75], v[74:75], v[76:77]
	ds_write_b64 v82, v[74:75]

;     ...
;     for (int u = vb; u < 1024; u += nb) {
;         const int r = u >> 8, v = u & 255, xcd = v >> 5, slot = v & 31, gq = slot & 3, rw = (r + ((slot >> 2) & 3)) & 3;
;         const int bh = xcd * 8 + 2 * r + (slot >> 4), bl = bh >> 4, head = bh & 15;
;         const int qt = (rw == 0) ? 15 - gq : (rw == 1) ? 8 + gq : (rw == 2) ? 7 - gq : gq;
;         const int q0 = qt * 256, nkt = 4 * qt + 4;
;         const int tlb = bl * 4096, gtb = half * HALF_T + tlb;
;         const int q1w = (((q0 + w * 32) >> 7) + 1) << 7;
;         const int qs0 = q0 + w * 32 + r16;
;         bf16x8 qf[6][2];
; #pragma unroll
;         for (int ds = 0; ds < 6; ++ds)
; #pragma unroll
;             for (int qb = 0; qb < 2; ++qb) qf[ds][qb] = *(const bf16x8*)(Q + (size_t)(tlb + qs0 + 16 * qb) * 3072 + head * 192 + ds * 32 + qq * 8);
;         int tminq = TMIN[(gtb + q0) >> 6];
; #pragma unroll
;         for (int i = 1; i < 4; ++i) tminq = min(tminq, TMIN[((gtb + q0) >> 6) + i]);
;         float m[2] = {-1e30f, -1e30f}, lsum[2] = {0.f, 0.f};
;         f32x4 ao[8][2];
; #pragma unroll
;         for (int d = 0; d < 8; ++d)
; #pragma unroll
;             for (int qb = 0; qb < 2; ++qb) ao[d][qb] = (f32x4){0.f, 0.f, 0.f, 0.f};
;         unsigned koff[3], kst[3], voff[2];
; #pragma unroll
;         for (int i = 0; i < 3; ++i) {
;             const int bb = 1024 * (3 * w + i) + 16 * l, rw = bb / 384, pc = (bb - 384 * rw) >> 4, c = (pc & 24) | ((pc ^ (2 * ((rw >> 1) & 1) + 4 * ((rw >> 4) & 1))) & 7);
;             if (c < 16) { koff[i] = (unsigned)(OFF_KN + ((size_t)(tlb + rw) * 2048 + head * 128 + c * 8) * 2); kst[i] = 64 * 2048 * 2; }
;             else { koff[i] = (unsigned)(OFF_KROPE + ((size_t)(gtb + rw) * 64 + (c - 16) * 8) * 2); kst[i] = 64 * 64 * 2; }
;         }
; #pragma unroll
;         for (int i = 0; i < 2; ++i) {
;             const int row = 8 * (2 * w + i) + (l >> 3), c = (l & 7) ^ ((row >> 1) & 7);
;             voff[i] = (unsigned)(OFF_VT + (((size_t)(bl * 2048 + head * 128 + row)) * 4096 + c * 8) * 2);
;         }
;         auto issue = [&](int kt, int st) {
;             char* sb = smem + st * AT_STAGE;
; #pragma unroll
;             for (int i = 0; i < 3; ++i)
.LBB0_930:
	s_or_b64 exec, exec, s[0:1]
	s_lshl_b32 s26, s21, 11
	s_lshl_b32 s0, s19, 7
	s_or_b32 s0, s0, s26
	v_add_u32_e32 v8, s0, v183
	v_lshl_add_u32 v230, v8, 13, v203
	v_add_u32_e32 v8, s0, v197
	v_lshl_add_u32 v229, v8, 13, v204
	v_add_u32_e32 v8, 16, v186
	v_add_u32_e32 v9, 0x400, v8
	v_readfirstlane_b32 s0, v8
	s_mov_b32 m0, s0
	v_readfirstlane_b32 s0, v9
	v_add_u32_e32 v8, 0x800, v8
	s_barrier
	global_load_lds_dwordx4 v178, s[22:23]
	s_mov_b32 m0, s0
	v_readfirstlane_b32 s0, v8
	v_add_u32_e32 v8, 16, v187
	v_add_u32_e32 v9, 0x6000, v8
	global_load_lds_dwordx4 v180, s[22:23]
	s_mov_b32 m0, s0
	v_readfirstlane_b32 s0, v9
	v_add_u32_e32 v8, 0x6400, v8
	global_load_lds_dwordx4 v182, s[22:23]
	s_mov_b32 m0, s0
	v_readfirstlane_b32 s0, v8
	global_load_lds_dwordx4 v230, s[22:23]
	s_mov_b32 m0, s0
	s_lshr_b32 s19, s34, 4
	global_load_lds_dwordx4 v229, s[22:23]
	v_mad_i64_i32 v[170:171], s[0:1], v6, s7, 0
	v_mad_i64_i32 v[168:169], s[0:1], v7, s7, 0
	s_lshl_b32 s35, s18, 2
	s_ashr_i32 s18, s8, 6
	s_and_b32 s0, s19, 1
	s_ashr_i32 s19, s18, 31
	s_and_b32 s27, s9, 8
	s_lshl_b32 s44, s0, 20
	s_lshl_b32 s45, s0, 7
	s_ashr_i32 s9, s8, 31
	s_addk_i32 s89, 0xc0
	s_lshl_b64 s[0:1], s[18:19], 2
	s_add_u32 s90, s0, 0x8441000
	s_addc_u32 s91, s1, 0
	s_add_i32 s27, s27, s20
	s_bfe_u32 s1, s27, 0x30001
	s_lshl_b32 s19, s1, 21
	s_lshl_b32 s0, s21, 24
	s_or_b32 s19, s44, s19
	s_or_b32 s0, s19, s0
	s_waitcnt vmcnt(5)
	v_min_i32_e32 v0, v0, v1
	v_add_u32_e32 v231, s0, v205
	s_lshl_b32 s0, s1, 8
	v_min3_i32 v223, v0, v2, v3
	v_add_u32_e32 v0, s8, v4
	s_or_b32 s0, s45, s0
	v_ashrrev_i32_e32 v1, 31, v0
	s_or_b32 s0, s0, s26
	v_and_b32_e32 v5, 0xffffff80, v5
	s_waitcnt vmcnt(0)
	v_lshl_add_u64 v[174:175], v[0:1], 2, s[36:37]
	v_add_u32_e32 v0, s0, v183
	v_mov_b32_e32 v2, v177
	v_mov_b32_e32 v3, v177
	v_add_u32_e32 v222, 0x80, v5
	v_lshl_add_u32 v232, v0, 13, v206
	v_mov_b32_e32 v176, v177
	v_mov_b32_e32 v0, v177
	v_mov_b32_e32 v1, v177
	v_mov_b64_e32 v[22:23], v[2:3]
	v_mov_b64_e32 v[18:19], v[2:3]
	v_mov_b64_e32 v[34:35], v[2:3]
	v_mov_b64_e32 v[30:31], v[2:3]
	v_mov_b64_e32 v[42:43], v[2:3]
	v_mov_b64_e32 v[38:39], v[2:3]
	v_mov_b64_e32 v[54:55], v[2:3]
	v_mov_b64_e32 v[50:51], v[2:3]
	v_mov_b64_e32 v[62:63], v[2:3]
	v_mov_b64_e32 v[46:47], v[2:3]
	v_mov_b64_e32 v[58:59], v[2:3]
	v_mov_b64_e32 v[10:11], v[2:3]
	v_mov_b64_e32 v[6:7], v[2:3]
	v_mov_b64_e32 v[26:27], v[2:3]
	v_mov_b64_e32 v[14:15], v[2:3]
	v_lshl_add_u64 v[184:185], s[8:9], 2, v[166:167]
	v_add_u32_e32 v233, v182, v228
	v_add_u32_e32 v234, v180, v227
	v_add_u32_e32 v235, v178, v226
	v_mov_b32_e32 v225, 0xf149f2ca
	s_mov_b32 s92, 0
	v_mov_b64_e32 v[20:21], v[0:1]
	v_mov_b64_e32 v[16:17], v[0:1]
	v_mov_b64_e32 v[32:33], v[0:1]
	v_mov_b64_e32 v[28:29], v[0:1]
	v_mov_b64_e32 v[40:41], v[0:1]
	v_mov_b64_e32 v[36:37], v[0:1]
	v_mov_b64_e32 v[52:53], v[0:1]
	v_mov_b64_e32 v[48:49], v[0:1]
	v_mov_b64_e32 v[60:61], v[0:1]
	v_mov_b64_e32 v[44:45], v[0:1]
	v_mov_b64_e32 v[56:57], v[0:1]
	v_mov_b64_e32 v[8:9], v[0:1]
	v_mov_b64_e32 v[4:5], v[0:1]
	v_mov_b64_e32 v[24:25], v[0:1]
	v_mov_b64_e32 v[12:13], v[0:1]
	v_mov_b32_e32 v224, 0xf149f2ca
	s_mov_b32 s0, 0
	v_mov_b64_e32 v[172:173], v[176:177]
	s_waitcnt vmcnt(0) lgkmcnt(0)
	s_barrier
; #define MFMA16(a, b, c) __builtin_amdgcn_mfma_f32_16x16x32_bf16((a), (b), (c), 0, 0, 0)
;     ...
;         auto issue = [&](int kt, int st) {
;             char* sb = smem + st * AT_STAGE;
; #pragma unroll
;             for (int i = 0; i < 3; ++i)
;                 __builtin_amdgcn_global_load_lds((const __attribute__((address_space(1))) void*)(P.ws + (koff[i] + (unsigned)kt * kst[i])), (__attribute__((address_space(3))) void*)(sb + (3 * w + i) * 1024), 16, 0, 0);
; #pragma unroll
;             for (int i = 0; i < 2; ++i)
;                 __builtin_amdgcn_global_load_lds((const __attribute__((address_space(1))) void*)(P.ws + (voff[i] + (unsigned)kt * 128u)), (__attribute__((address_space(3))) void*)(sb + AT_KB + (2 * w + i) * 1024), 16, 0, 0);
;         };
;         __syncthreads();
;         issue(0, 0); asm volatile("s_waitcnt vmcnt(0)" ::: "memory"); __syncthreads();
;         for (int kt = 0; kt < nkt; ++kt) {
;             const bool more = kt + 1 < nkt;
;             if (more) issue(kt + 1, (kt + 1) & 1);
;             const char* sb = smem + (kt & 1) * AT_STAGE;
;             if (kt * 64 < q1w) {
;             f32x4 as[4][2];
; #pragma unroll
;             for (int kb = 0; kb < 4; ++kb)
; #pragma unroll
;                 for (int qb = 0; qb < 2; ++qb) as[kb][qb] = (f32x4){0.f, 0.f, 0.f, 0.f};
; #pragma unroll
;             for (int ds = 0; ds < 6; ++ds) {
;                 const int ch = 4 * ds + qq;
; #pragma unroll
;                 for (int kb = 0; kb < 4; ++kb) {
;                     const int krow = krow0 + 32 * (kb >> 1) + 4 * (kb & 1), key = kkey;
;                     const bf16x8 kf = *(const bf16x8*)(sb + krow * 384 + (((ch & 24) | ((ch ^ key) & 7)) << 4));
; #pragma unroll
;                     for (int qb = 0; qb < 2; ++qb) as[kb][qb] = MFMA16(kf, qf[ds][qb], as[kb][qb]);
;                 }
;             }
;             const bool need_mask = (kt >= 4 * qt) || (TMAX[((gtb) >> 6) + kt] > tminq);
.LBB0_931:
	s_add_u32 s98, s22, s90
	s_addc_u32 s99, s23, s91
	global_load_dword v251, v177, s[98:99]
	s_add_i32 s88, s0, 1
	s_bitcmp1_b32 s88, 0
	s_cselect_b32 s1, 0xa000, 0
	s_add_i32 s19, s1, 16
	v_readfirstlane_b32 s100, v186
	v_readfirstlane_b32 s101, v187
	v_cmp_lt_i32_e32 vcc, s92, v222
	s_add_i32 s100, s100, s19
	s_add_i32 s101, s101, s19
	s_and_saveexec_b64 s[26:27], vcc
	s_cbranch_execz .Lattn_skip_dma
	s_bitcmp1_b32 s0, 0
	s_cselect_b32 s1, 0xa000, 0
	s_add_i32 s93, s1, 16
	v_add3_u32 v148, s93, v198, v199
	v_add3_u32 v152, s93, v200, v199
	ds_read_b128 v[144:147], v148
	ds_read_b128 v[236:239], v148 offset:1536
	ds_read_b128 v[240:243], v148 offset:12288
	ds_read_b128 v[244:247], v148 offset:13824
	s_cmp_ge_u32 s0, s35
	s_cselect_b64 s[0:1], -1, 0
	s_and_b64 vcc, exec, s[0:1]
	v_add3_u32 v248, s93, v188, v201
	v_add3_u32 v250, s93, v188, v202
	s_waitcnt lgkmcnt(3)
	v_mfma_f32_16x16x32_bf16 v[128:131], v[144:147], v[104:107], 0
	v_mfma_f32_16x16x32_bf16 v[116:119], v[144:147], v[108:111], 0
	s_mov_b32 m0, s100
	ds_read_b128 v[144:147], v152
	global_load_lds_dwordx4 v235, s[22:23]
	s_waitcnt lgkmcnt(3)
	v_mfma_f32_16x16x32_bf16 v[124:127], v[236:239], v[104:107], 0
	v_mfma_f32_16x16x32_bf16 v[112:115], v[236:239], v[108:111], 0
	s_add_i32 m0, s100, 0x400
	ds_read_b128 v[236:239], v152 offset:1536
	global_load_lds_dwordx4 v234, s[22:23]
	s_waitcnt lgkmcnt(3)
	v_mfma_f32_16x16x32_bf16 v[132:135], v[240:243], v[104:107], 0
	v_mfma_f32_16x16x32_bf16 v[120:123], v[240:243], v[108:111], 0
	s_add_i32 m0, s100, 0x800
	ds_read_b128 v[240:243], v152 offset:12288
	global_load_lds_dwordx4 v233, s[22:23]
	s_waitcnt lgkmcnt(3)
	v_mfma_f32_16x16x32_bf16 v[140:143], v[244:247], v[104:107], 0
	v_mfma_f32_16x16x32_bf16 v[136:139], v[244:247], v[108:111], 0
	s_add_i32 m0, s101, 0x6000
	ds_read_b128 v[244:247], v152 offset:13824
	global_load_lds_dwordx4 v232, s[22:23]
	s_waitcnt lgkmcnt(3)
	v_mfma_f32_16x16x32_bf16 v[128:131], v[144:147], v[96:99], v[128:131]
	v_mfma_f32_16x16x32_bf16 v[116:119], v[144:147], v[100:103], v[116:119]
	s_add_i32 m0, s101, 0x6400
	ds_read_b128 v[144:147], v148 offset:128
	global_load_lds_dwordx4 v231, s[22:23]
	s_waitcnt lgkmcnt(3)
	v_mfma_f32_16x16x32_bf16 v[124:127], v[236:239], v[96:99], v[124:127]
	v_mfma_f32_16x16x32_bf16 v[112:115], v[236:239], v[100:103], v[112:115]
	ds_read_b128 v[236:239], v148 offset:1664
	s_waitcnt lgkmcnt(3)
	v_mfma_f32_16x16x32_bf16 v[132:135], v[240:243], v[96:99], v[132:135]
	v_mfma_f32_16x16x32_bf16 v[120:123], v[240:243], v[100:103], v[120:123]
	ds_read_b128 v[240:243], v148 offset:12416
	s_waitcnt lgkmcnt(3)
	v_mfma_f32_16x16x32_bf16 v[140:143], v[244:247], v[96:99], v[140:143]
	v_mfma_f32_16x16x32_bf16 v[136:139], v[244:247], v[100:103], v[136:139]
	ds_read_b128 v[244:247], v148 offset:13952
	s_waitcnt lgkmcnt(3)
	v_mfma_f32_16x16x32_bf16 v[128:131], v[144:147], v[88:91], v[128:131]
	v_mfma_f32_16x16x32_bf16 v[116:119], v[144:147], v[92:95], v[116:119]
	ds_read_b128 v[144:147], v152 offset:128
	s_waitcnt lgkmcnt(3)
	v_mfma_f32_16x16x32_bf16 v[124:127], v[236:239], v[88:91], v[124:127]
	v_mfma_f32_16x16x32_bf16 v[112:115], v[236:239], v[92:95], v[112:115]
	ds_read_b128 v[236:239], v152 offset:1664
	s_waitcnt lgkmcnt(3)
	v_mfma_f32_16x16x32_bf16 v[132:135], v[240:243], v[88:91], v[132:135]
	v_mfma_f32_16x16x32_bf16 v[120:123], v[240:243], v[92:95], v[120:123]
	ds_read_b128 v[240:243], v152 offset:12416
	s_waitcnt lgkmcnt(3)
	v_mfma_f32_16x16x32_bf16 v[140:143], v[244:247], v[88:91], v[140:143]
	v_mfma_f32_16x16x32_bf16 v[136:139], v[244:247], v[92:95], v[136:139]
	ds_read_b128 v[244:247], v152 offset:13952
	s_waitcnt lgkmcnt(3)
	v_mfma_f32_16x16x32_bf16 v[128:131], v[144:147], v[80:83], v[128:131]
	v_mfma_f32_16x16x32_bf16 v[116:119], v[144:147], v[84:87], v[116:119]
	ds_read_b128 v[144:147], v148 offset:256
	s_waitcnt lgkmcnt(3)
	v_mfma_f32_16x16x32_bf16 v[124:127], v[236:239], v[80:83], v[124:127]
	v_mfma_f32_16x16x32_bf16 v[112:115], v[236:239], v[84:87], v[112:115]
	ds_read_b128 v[236:239], v148 offset:1792
	s_waitcnt lgkmcnt(3)
	v_mfma_f32_16x16x32_bf16 v[132:135], v[240:243], v[80:83], v[132:135]
	v_mfma_f32_16x16x32_bf16 v[120:123], v[240:243], v[84:87], v[120:123]
	ds_read_b128 v[240:243], v148 offset:12544
	s_waitcnt lgkmcnt(3)
	v_mfma_f32_16x16x32_bf16 v[140:143], v[244:247], v[80:83], v[140:143]
	v_mfma_f32_16x16x32_bf16 v[136:139], v[244:247], v[84:87], v[136:139]
	ds_read_b128 v[244:247], v148 offset:14080
	s_waitcnt lgkmcnt(3)
	v_mfma_f32_16x16x32_bf16 v[128:131], v[144:147], v[72:75], v[128:131]
	v_mfma_f32_16x16x32_bf16 v[116:119], v[144:147], v[76:79], v[116:119]
	ds_read_b128 v[144:147], v152 offset:256
	s_waitcnt lgkmcnt(3)
	v_mfma_f32_16x16x32_bf16 v[124:127], v[236:239], v[72:75], v[124:127]
	v_mfma_f32_16x16x32_bf16 v[112:115], v[236:239], v[76:79], v[112:115]
	ds_read_b128 v[236:239], v152 offset:1792
	s_waitcnt lgkmcnt(3)
	v_mfma_f32_16x16x32_bf16 v[132:135], v[240:243], v[72:75], v[132:135]
	v_mfma_f32_16x16x32_bf16 v[120:123], v[240:243], v[76:79], v[120:123]
	ds_read_b128 v[240:243], v152 offset:12544
	s_waitcnt lgkmcnt(3)
	v_mfma_f32_16x16x32_bf16 v[140:143], v[244:247], v[72:75], v[140:143]
	v_mfma_f32_16x16x32_bf16 v[136:139], v[244:247], v[76:79], v[136:139]
	ds_read_b128 v[244:247], v152 offset:14080
	s_waitcnt lgkmcnt(3)
	v_mfma_f32_16x16x32_bf16 v[128:131], v[144:147], v[64:67], v[128:131]
	v_mfma_f32_16x16x32_bf16 v[116:119], v[144:147], v[68:71], v[116:119]
	s_waitcnt lgkmcnt(2)
	v_mfma_f32_16x16x32_bf16 v[124:127], v[236:239], v[64:67], v[124:127]
	v_mfma_f32_16x16x32_bf16 v[112:115], v[236:239], v[68:71], v[112:115]
	ds_read_b128 v[236:239], v248 offset:24576
	s_waitcnt lgkmcnt(2)
	v_mfma_f32_16x16x32_bf16 v[132:135], v[240:243], v[64:67], v[132:135]
	v_mfma_f32_16x16x32_bf16 v[120:123], v[240:243], v[68:71], v[120:123]
	ds_read_b128 v[240:243], v248 offset:26624
	s_waitcnt lgkmcnt(2)
	v_mfma_f32_16x16x32_bf16 v[140:143], v[244:247], v[64:67], v[140:143]
	v_mfma_f32_16x16x32_bf16 v[136:139], v[244:247], v[68:71], v[136:139]
	ds_read_b128 v[244:247], v248 offset:28672
	s_cbranch_vccnz .LBB0_934
	s_waitcnt vmcnt(5)
	v_cmp_gt_i32_e64 s[0:1], v251, v223

;     ...
;         auto issue = [&](int kt, int st) {
;             char* sb = smem + st * AT_STAGE;
; #pragma unroll
;             for (int i = 0; i < 3; ++i)
;                 __builtin_amdgcn_global_load_lds((const __attribute__((address_space(1))) void*)(P.ws + (koff[i] + (unsigned)kt * kst[i])), (__attribute__((address_space(3))) void*)(sb + (3 * w + i) * 1024), 16, 0, 0);
; #pragma unroll
;             for (int i = 0; i < 2; ++i)
;                 __builtin_amdgcn_global_load_lds((const __attribute__((address_space(1))) void*)(P.ws + (voff[i] + (unsigned)kt * 128u)), (__attribute__((address_space(3))) void*)(sb + AT_KB + (2 * w + i) * 1024), 16, 0, 0);
;         };
;         __syncthreads();
;         issue(0, 0); asm volatile("s_waitcnt vmcnt(0)" ::: "memory"); __syncthreads();
;         for (int kt = 0; kt < nkt; ++kt) {
;             const bool more = kt + 1 < nkt;
;             if (more) issue(kt + 1, (kt + 1) & 1);
.Lattn_skip_dma:
	s_mov_b64 exec, s[26:27]
	s_mov_b32 m0, s100
	s_nop 0
	global_load_lds_dwordx4 v235, s[22:23]
	s_add_i32 m0, s100, 0x400
	s_nop 0
	global_load_lds_dwordx4 v234, s[22:23]
	s_add_i32 m0, s100, 0x800
	s_nop 0
	global_load_lds_dwordx4 v233, s[22:23]
	s_add_i32 m0, s101, 0x6000
	s_nop 0
	global_load_lds_dwordx4 v232, s[22:23]
	s_add_i32 m0, s101, 0x6400
	s_nop 0
	global_load_lds_dwordx4 v231, s[22:23]
	s_branch .LBB0_939
